# SSD backward pass: forward-result and gate row loads issued after barrier 2 instead of at the finalize (ssd_pf), stacked on the wait-count fixes and LRU carry
# speedup vs baseline: 1.0054x; 1.0021x over previous
; __device__ __forceinline__ void ssd_phase(const Args& A, unsigned char* smem, const bool dry) {
;     ...
;                 __syncthreads();
;                 { const int j = tid >> 3, p8 = (tid & 7) * 8; float f[8]; unpack8(*(const u32x4*)(Xb + j * 72 + p8), f); const float w = wv[j];
; #pragma unroll
;                     for (int e = 0; e < 8; ++e) f[e] *= w;
;                     *(u32x4*)(XWb + j * 72 + p8) = pack8(f); }
;                 f32x4 yst[2];
;                 {
;                     bf16x8 cf[4], bfr[2][4], sf[2][4];
; #pragma unroll
;                     for (int ks = 0; ks < 4; ++ks) cf[ks] = *(const bf16x8*)(Cb + (16 * it + r16) * 136 + 32 * ks + 8 * q4);
; #pragma unroll
;                     for (int jj = 0; jj < 2; ++jj)
; #pragma unroll
;                         for (int ks = 0; ks < 4; ++ks) bfr[jj][ks] = *(const bf16x8*)(Bb + (16 * (2 * hh + jj) + r16) * 136 + 32 * ks + 8 * q4);
; #pragma unroll
;                     for (int pp = 0; pp < 2; ++pp)
; #pragma unroll
;                         for (int ks = 0; ks < 4; ++ks) sf[pp][ks] = *(const bf16x8*)(Sb + (16 * (2 * hh + pp) + r16) * 136 + 32 * ks + 8 * q4);
;                     const int i = 16 * it + r16; const float ci = cumv[i];
;                     f32x4 cj[2], dj[2];
; #pragma unroll
;                     for (int jj = 0; jj < 2; ++jj) { cj[jj] = *(const f32x4*)(cumv + 16 * (2 * hh + jj) + 4 * q4); dj[jj] = *(const f32x4*)(dtv + 16 * (2 * hh + jj) + 4 * q4); }
;                     __builtin_amdgcn_sched_barrier(0);
;                     f32x4 gacc[2];
; #pragma unroll
;                     for (int jj = 0; jj < 2; ++jj) { gacc[jj] = (f32x4){0.f, 0.f, 0.f, 0.f};
; #pragma unroll
;                         for (int ks = 0; ks < 4; ++ks) gacc[jj] = __builtin_amdgcn_mfma_f32_16x16x32_bf16(bfr[jj][ks], cf[ks], gacc[jj], 0, 0, 0); }
; #pragma unroll
;                     for (int pp = 0; pp < 2; ++pp) { yst[pp] = (f32x4){0.f, 0.f, 0.f, 0.f};
; #pragma unroll
;                         for (int ks = 0; ks < 4; ++ks) yst[pp] = __builtin_amdgcn_mfma_f32_16x16x32_bf16(cf[ks], sf[pp][ks], yst[pp], 0, 0, 0); }
; #pragma unroll
;                     for (int jj = 0; jj < 2; ++jj) { const int jt = 2 * hh + jj; float m[4];
; #pragma unroll
.LBB0_478:
	v_lshlrev_b32_e32 v46, 1, v44
	v_add3_u32 v53, s7, v84, v46
	s_waitcnt lgkmcnt(0)
	s_barrier
	ds_read_b128 v[36:39], v53 offset:52224
	ds_read_b32 v40, v83
	s_waitcnt lgkmcnt(1)
	v_lshlrev_b32_e32 v42, 16, v36
	v_and_b32_e32 v43, 0xffff0000, v36
	v_lshlrev_b32_e32 v36, 16, v37
	v_and_b32_e32 v37, 0xffff0000, v37
	s_waitcnt lgkmcnt(0)
	v_pk_mul_f32 v[70:71], v[40:41], v[36:37] op_sel_hi:[0,1]
	v_lshlrev_b32_e32 v36, 16, v38
	v_and_b32_e32 v37, 0xffff0000, v38
	v_pk_mul_f32 v[72:73], v[40:41], v[36:37] op_sel_hi:[0,1]
	v_lshlrev_b32_e32 v36, 16, v39
	v_and_b32_e32 v37, 0xffff0000, v39
	v_pk_mul_f32 v[42:43], v[40:41], v[42:43] op_sel_hi:[0,1]
	v_pk_mul_f32 v[40:41], v[40:41], v[36:37] op_sel_hi:[0,1]
	v_cvt_pk_bf16_f32 v36, v42, v43
	v_cvt_pk_bf16_f32 v37, v70, v71
	v_cvt_pk_bf16_f32 v38, v72, v73
	v_cvt_pk_bf16_f32 v39, v40, v41
	ds_write_b128 v85, v[36:39]
	ds_read_b128 v[40:43], v154 offset:64
	ds_read_b128 v[70:73], v154 offset:128
	ds_read_b128 v[36:39], v155 offset:17472
	ds_read_b128 v[74:77], v155 offset:17536
	ds_read_b128 v[170:173], v155 offset:17600
	ds_read_b128 v[174:177], v155 offset:21760
	ds_read_b128 v[178:181], v155 offset:21824
	ds_read_b128 v[182:185], v155 offset:21888
	ds_read_b128 v[186:189], v155 offset:21952
	ds_read_b128 v[190:193], v154 offset:192
	ds_read_b128 v[194:197], v155 offset:34816
	ds_read_b128 v[198:201], v155 offset:34880
	ds_read_b128 v[202:205], v155 offset:34944
	ds_read_b128 v[206:209], v155 offset:35008
	ds_read_b128 v[210:213], v155 offset:39168
	ds_read_b128 v[214:217], v155 offset:39232
	ds_read_b128 v[218:221], v155 offset:39296
	ds_read_b128 v[222:225], v155 offset:17408
	ds_read_b128 v[226:229], v155 offset:39360
	ds_read_b32 v169, v87
	ds_read_b128 v[230:233], v135
	ds_read_b128 v[234:237], v136
	ds_read_b128 v[238:241], v135 offset:64
	ds_read_b128 v[242:245], v154
	ds_read_b128 v[246:249], v136 offset:64
	s_waitcnt lgkmcnt(1)
	v_mfma_f32_16x16x32_bf16 v[222:225], v[222:225], v[242:245], 0
	v_sub_f32_e32 v78, v169, v230
	v_mul_f32_e32 v78, 0x3fb8aa3b, v78
	v_exp_f32_e32 v79, v78
	v_mfma_f32_16x16x32_bf16 v[36:39], v[36:39], v[40:43], v[222:225]
	v_sub_f32_e32 v78, v169, v231
	v_mul_f32_e32 v78, 0x3fb8aa3b, v78
	v_mfma_f32_16x16x32_bf16 v[36:39], v[74:77], v[70:73], v[36:39]
	s_nop 0
	v_exp_f32_e32 v222, v78
	v_sub_f32_e32 v78, v169, v232
	v_mul_f32_e32 v74, 0x3fb8aa3b, v78
	v_mfma_f32_16x16x32_bf16 v[36:39], v[170:173], v[190:193], v[36:39]
	v_exp_f32_e32 v78, v74
	v_sub_f32_e32 v223, v169, v233
	v_mfma_f32_16x16x32_bf16 v[74:77], v[174:177], v[242:245], 0
	v_mfma_f32_16x16x32_bf16 v[74:77], v[178:181], v[40:43], v[74:77]
	s_nop 3
	v_mul_f32_e32 v36, v79, v36
	v_mul_f32_e32 v36, v234, v36
	v_cndmask_b32_e64 v170, v36, 0, s[58:59]
	v_mul_f32_e32 v36, 0x3fb8aa3b, v223
	v_exp_f32_e32 v79, v36
	v_mul_f32_e32 v37, v222, v37
	v_mul_f32_e32 v36, v235, v37
	v_cndmask_b32_e64 v171, 0, v36, s[60:61]
	v_pk_mul_f32 v[36:37], v[78:79], v[38:39]
	v_cvt_pk_bf16_f32 v170, v170, v171
	v_pk_mul_f32 v[78:79], v[236:237], v[36:37]
	v_mfma_f32_16x16x32_bf16 v[36:39], v[182:185], v[70:73], v[74:77]
	v_cvt_pk_bf16_f32 v78, v78, v79
	v_cndmask_b32_e64 v79, v78, 0, s[64:65]
	v_mfma_f32_16x16x32_bf16 v[74:77], v[186:189], v[190:193], v[36:39]
	s_nop 4
	v_lshrrev_b32_e32 v36, 16, v78
	v_sub_f32_e32 v78, v169, v238
	v_mul_f32_e32 v78, 0x3fb8aa3b, v78
	v_exp_f32_e32 v78, v78
	v_cndmask_b32_e64 v36, v36, 0, s[62:63]
	v_perm_b32 v171, v36, v79, s31
	v_add_u32_e32 v79, v89, v90
	v_mul_f32_e32 v74, v78, v74
	v_sub_f32_e32 v78, v169, v239
	v_mul_f32_e32 v78, 0x3fb8aa3b, v78
	v_exp_f32_e32 v78, v78
	v_mfma_f32_16x16x32_bf16 v[36:39], v[242:245], v[194:197], 0
	ds_write_b64 v79, v[170:171]
	s_waitcnt lgkmcnt(1)
	v_mul_f32_e32 v74, v246, v74
	v_cndmask_b32_e64 v79, v74, 0, s[66:67]
	v_mfma_f32_16x16x32_bf16 v[170:173], v[242:245], v[210:213], 0
	v_mul_f32_e32 v78, v78, v75
	v_sub_f32_e32 v74, v169, v240
	v_sub_f32_e32 v75, v169, v241
	v_mfma_f32_16x16x32_bf16 v[36:39], v[40:43], v[198:201], v[36:39]
	v_mul_f32_e32 v74, 0x3fb8aa3b, v74
	v_mul_f32_e32 v75, 0x3fb8aa3b, v75
	v_exp_f32_e32 v74, v74
	v_mfma_f32_16x16x32_bf16 v[40:43], v[40:43], v[214:217], v[170:173]
	v_exp_f32_e32 v75, v75
	v_mfma_f32_16x16x32_bf16 v[36:39], v[70:73], v[202:205], v[36:39]
	v_mfma_f32_16x16x32_bf16 v[40:43], v[70:73], v[218:221], v[40:43]
	v_mul_f32_e32 v70, v247, v78
	v_cndmask_b32_e64 v72, 0, v70, s[68:69]
	v_pk_mul_f32 v[70:71], v[74:75], v[76:77]
	v_cvt_pk_bf16_f32 v72, v79, v72
	v_pk_mul_f32 v[70:71], v[248:249], v[70:71]
	v_add_u32_e32 v78, v88, v86
	v_cvt_pk_bf16_f32 v70, v70, v71
	v_cndmask_b32_e64 v71, v70, 0, s[72:73]
	v_lshrrev_b32_e32 v70, 16, v70
	v_cndmask_b32_e64 v70, v70, 0, s[70:71]
	v_perm_b32 v73, v70, v71, s31
	v_add_u32_e32 v70, s7, v90
	v_mfma_f32_16x16x32_bf16 v[36:39], v[190:193], v[206:209], v[36:39]
	ds_write_b64 v156, v[72:73]
	s_waitcnt lgkmcnt(0)
	s_barrier
; __device__ __forceinline__ void unpack8(const u32x4 v, float* f) { f[0] = bf_lo(v.x); f[1] = bf_hi(v.x); f[2] = bf_lo(v.y); f[3] = bf_hi(v.y); f[4] = bf_lo(v.z); f[5] = bf_hi(v.z); f[6] = bf_lo(v.w); f[7] = bf_hi(v.w); }
; __device__ __forceinline__ void ssd_phase(const Args& A, unsigned char* smem, const bool dry) {
;     ...
;                 __syncthreads();
;                 {
;                     bf16x8 mf[2], xf[2][2], af[2], xwf[4][2];
; #pragma unroll
;                     for (int ks = 0; ks < 2; ++ks) mf[ks] = *(const bf16x8*)(Mb + (16 * it + r16) * 72 + 32 * ks + 8 * q4);
; #pragma unroll
;                     for (int pp = 0; pp < 2; ++pp)
; #pragma unroll
;                         for (int ks = 0; ks < 2; ++ks) xf[pp][ks] = tr_frag(Xb, 72, 32 * ks, 16 * (2 * hh + pp), lane);
; #pragma unroll
;                     for (int ks = 0; ks < 2; ++ks) af[ks] = tr_frag(Bb, 136, 32 * ks, 16 * wave, lane);
; #pragma unroll
;                     for (int pt = 0; pt < 4; ++pt)
; #pragma unroll
;                         for (int ks = 0; ks < 2; ++ks) xwf[pt][ks] = tr_frag(XWb, 72, 32 * ks, 16 * pt, lane);
;                     const f32x4 ec = *(const f32x4*)(ecv + 16 * it + 4 * q4); const float et = etot[0];
;     ...
;                         float yf[8], z[8]; unpack8(*(const u32x4*)(tmp1 + tok * 1024 + 64 * h + p8), yf);
;                         u16* zp = proj + tok * PLD + 3072 + 64 * h + p8; unpack8(*(const u32x4*)zp, z);
	v_add3_u32 v79, v70, v91, v137
	ds_read_b128 v[70:73], v78 offset:64
	ds_read_b64_tr_b16 v[74:75], v79 offset:52224
	ds_read_b64_tr_b16 v[76:77], v79 offset:52800
	ds_read_b64_tr_b16 v[170:171], v79 offset:56832
	ds_read_b64_tr_b16 v[176:177], v79 offset:52832
	ds_read_b64_tr_b16 v[174:175], v79 offset:52256
	ds_read_b64_tr_b16 v[172:173], v79 offset:57408
	ds_read_b64_tr_b16 v[180:181], v79 offset:57440
	ds_read_b64_tr_b16 v[182:183], v157 offset:17408
	ds_read_b64_tr_b16 v[178:179], v79 offset:56864
	ds_read_b64_tr_b16 v[184:185], v157 offset:18496
	ds_read_b64_tr_b16 v[186:187], v157 offset:26112
	ds_read_b64_tr_b16 v[188:189], v157 offset:27200
	ds_read_b64_tr_b16 v[194:195], v158
	ds_read_b64_tr_b16 v[196:197], v158 offset:576
	ds_read_b64_tr_b16 v[198:199], v158 offset:32
	ds_read_b64_tr_b16 v[202:203], v158 offset:64
	ds_read_b64_tr_b16 v[206:207], v158 offset:96
	ds_read_b64_tr_b16 v[210:211], v158 offset:4608
	ds_read_b64_tr_b16 v[200:201], v158 offset:608
	ds_read_b64_tr_b16 v[204:205], v158 offset:640
	ds_read_b64_tr_b16 v[208:209], v158 offset:672
	ds_read_b64_tr_b16 v[212:213], v158 offset:5184
	ds_read_b64_tr_b16 v[214:215], v158 offset:4640
	ds_read_b64_tr_b16 v[218:219], v158 offset:4672
	ds_read_b64_tr_b16 v[222:223], v158 offset:4704
	ds_read_b128 v[230:233], v78
	ds_read_b128 v[234:237], v92
	v_mov_b32_e32 v78, s30
	ds_read_b64_tr_b16 v[216:217], v158 offset:5216
	ds_read_b64_tr_b16 v[220:221], v158 offset:5248
	ds_read_b64_tr_b16 v[224:225], v158 offset:5280
	ds_read_b32 v78, v78
	s_cmp_eq_u64 s[10:11], 0
	s_cbranch_scc1 .Lssd_pf_skip
	v_add_u32_e32 v238, s22, v99
	v_add_u32_e32 v239, s23, v82
	v_cndmask_b32_e64 v238, v238, v239, s[92:93]
	v_add_u32_e32 v240, s40, v238
	v_ashrrev_i32_e32 v241, 31, v240
	v_lshlrev_b64 v[238:239], 11, v[240:241]
	v_lshl_add_u64 v[238:239], v[56:57], 0, v[238:239]
	v_mov_b64_e32 v[246:247], s[96:97]
	v_mad_i64_i32 v[240:241], s[14:15], v240, s33, v[246:247]
	v_lshlrev_b32_e32 v246, 1, v44
	v_add_u32_e32 v246, s6, v246
	v_mov_b32_e32 v247, 0
	v_lshl_add_u64 v[240:241], v[240:241], 0, v[246:247]
	v_add_co_u32_e32 v240, vcc, 0x1000, v240
	s_nop 1
	v_addc_co_u32_e32 v241, vcc, 0, v241, vcc
	global_load_dwordx4 v[242:245], v[238:239], off
	s_nop 0
	global_load_dwordx4 v[246:249], v[240:241], off offset:2048
; __device__ __forceinline__ void ssd_phase(const Args& A, unsigned char* smem, const bool dry) {
;     ...
;                     __builtin_amdgcn_sched_barrier(0);
; #pragma unroll
;                     for (int pt = 0; pt < 4; ++pt) Sacc[pt] = Sacc[pt] * et;
;                     f32x4 yin[2];
; #pragma unroll
;                     for (int pp = 0; pp < 2; ++pp) { yin[pp] = (f32x4){0.f, 0.f, 0.f, 0.f};
; #pragma unroll
;                         for (int ks = 0; ks < 2; ++ks) yin[pp] = __builtin_amdgcn_mfma_f32_16x16x32_bf16(mf[ks], xf[pp][ks], yin[pp], 0, 0, 0); }
; #pragma unroll
;                     for (int pt = 0; pt < 4; ++pt)
; #pragma unroll
;                         for (int ks = 0; ks < 2; ++ks) Sacc[pt] = __builtin_amdgcn_mfma_f32_16x16x32_bf16(af[ks], xwf[pt][ks], Sacc[pt], 0, 0, 0);
; #pragma unroll
;                     for (int pp = 0; pp < 2; ++pp) { const int pt = 2 * hh + pp;
; #pragma unroll
;                         for (int r = 0; r < 4; ++r) { const int i = 16 * it + 4 * q4 + r; yb[i * 64 + 16 * pt + r16] = yin[pp][r] + ec[r] * yst[pp][r]; } }
; #pragma unroll
;                     for (int pt = 0; pt < 4; ++pt) { u32x2 w; w.x = pk2(Sacc[pt][0], Sacc[pt][1]); w.y = pk2(Sacc[pt][2], Sacc[pt][3]);
;                         *(u32x2*)(Sb + (16 * pt + r16) * 136 + 16 * wave + 4 * q4) = w; }
;                 }
;                 __syncthreads();
;                 { const int i = tid >> 3, p8 = (tid & 7) * 8; const int t = dir ? (SEQ - 1 - (bt * 64 + i)) : (bt * 64 + i); const size_t tok = (size_t)(b * SEQ + t);
;                     float y[8];
; #pragma unroll
;                     for (int j = 0; j < 8; ++j) y[j] = yb[i * 64 + p8 + j];
;                     if (dir == 0) {
;                         { float xf[8]; unpack8(*(const u32x4*)(Xb + i * 72 + p8), xf);
; #pragma unroll
;                         for (int j = 0; j < 8; ++j) y[j] += Dh * xf[j]; }
;                         if (!dry) *(u32x4*)(tmp1 + tok * 1024 + 64 * h + p8) = pack8(y);
;                     } else {
;                         float yf[8], z[8]; unpack8(*(const u32x4*)(tmp1 + tok * 1024 + 64 * h + p8), yf);
;                         u16* zp = proj + tok * PLD + 3072 + 64 * h + p8; unpack8(*(const u32x4*)zp, z);
; #pragma unroll
;                         for (int j = 0; j < 8; ++j) y[j] = (y[j] + yf[j]) * siluf_(z[j]);
;                         if (!dry) *(u32x4*)zp = pack8(y);
.Lssd_pf_skip:
	v_mfma_f32_16x16x32_bf16 v[40:43], v[190:193], v[226:229], v[40:43]
	s_waitcnt lgkmcnt(5)
	v_mfma_f32_16x16x32_bf16 v[74:77], v[230:233], v[74:77], 0
	s_waitcnt lgkmcnt(0)
	v_pk_mul_f32 v[22:23], v[22:23], v[78:79] op_sel_hi:[1,0]
	v_pk_mul_f32 v[20:21], v[20:21], v[78:79] op_sel_hi:[1,0]
	v_pk_mul_f32 v[26:27], v[26:27], v[78:79] op_sel_hi:[1,0]
	v_mfma_f32_16x16x32_bf16 v[74:77], v[70:73], v[170:173], v[74:77]
	v_mul_f32_e64 v24, v24, v78
	v_mul_f32_e64 v25, v25, v78
	v_pk_mul_f32 v[30:31], v[30:31], v[78:79] op_sel_hi:[1,0]
	v_pk_mul_f32 v[28:29], v[28:29], v[78:79] op_sel_hi:[1,0]
	v_mfma_f32_16x16x32_bf16 v[170:173], v[230:233], v[174:177], 0
	v_mul_f32_e64 v34, v34, v78
	v_mul_f32_e64 v35, v35, v78
	v_pk_mul_f32 v[32:33], v[32:33], v[78:79] op_sel_hi:[1,0]
	v_fma_f32 v36, v36, v234, v74
	v_mfma_f32_16x16x32_bf16 v[20:23], v[182:185], v[194:197], v[20:23]
	v_fmac_f32_e32 v77, v39, v237
	v_fma_f32 v37, v37, v235, v75
	v_fma_f32 v38, v38, v236, v76
	v_mfma_f32_16x16x32_bf16 v[70:73], v[70:73], v[178:181], v[170:173]
	s_mov_b64 s[14:15], -1
	s_and_b64 vcc, exec, s[10:11]
	v_mfma_f32_16x16x32_bf16 v[24:27], v[182:185], v[198:201], v[24:27]
	v_mfma_f32_16x16x32_bf16 v[28:31], v[182:185], v[202:205], v[28:31]
	s_nop 3
	v_fma_f32 v39, v40, v234, v70
	ds_write2_b32 v159, v36, v39 offset1:16
	v_fma_f32 v36, v41, v235, v71
	v_mfma_f32_16x16x32_bf16 v[32:35], v[182:185], v[206:209], v[32:35]
	ds_write2_b32 v159, v37, v36 offset0:64 offset1:80
	v_fma_f32 v36, v42, v236, v72
	ds_write2_b32 v159, v38, v36 offset0:128 offset1:144
	v_mfma_f32_16x16x32_bf16 v[20:23], v[186:189], v[210:213], v[20:23]
	v_fmac_f32_e32 v73, v43, v237
	ds_write2_b32 v159, v77, v73 offset0:192 offset1:208
	v_mfma_f32_16x16x32_bf16 v[24:27], v[186:189], v[214:217], v[24:27]
	v_mfma_f32_16x16x32_bf16 v[28:31], v[186:189], v[218:221], v[28:31]
	s_nop 3
	v_cvt_pk_bf16_f32 v36, v20, v21
	v_cvt_pk_bf16_f32 v37, v22, v23
	ds_write_b64 v160, v[36:37] offset:34816
	v_mfma_f32_16x16x32_bf16 v[32:35], v[186:189], v[222:225], v[32:35]
	v_cvt_pk_bf16_f32 v36, v24, v25
	v_cvt_pk_bf16_f32 v37, v26, v27
	ds_write_b64 v160, v[36:37] offset:39168
	v_cvt_pk_bf16_f32 v36, v28, v29
	v_cvt_pk_bf16_f32 v37, v30, v31
	ds_write_b64 v160, v[36:37] offset:43520
	s_nop 1
	v_cvt_pk_bf16_f32 v36, v32, v33
	v_cvt_pk_bf16_f32 v37, v34, v35
	ds_write_b64 v160, v[36:37] offset:47872
	v_add_u32_e32 v36, s22, v99
	v_add_u32_e32 v37, s23, v82
	v_cndmask_b32_e64 v36, v36, v37, s[92:93]
	s_waitcnt lgkmcnt(0)
	s_barrier
	v_add_u32_e32 v72, s40, v36
	ds_read_b128 v[40:43], v93
	ds_read_b128 v[36:39], v93 offset:16
	v_ashrrev_i32_e32 v73, 31, v72
	v_lshlrev_b64 v[70:71], 11, v[72:73]
	v_lshl_add_u64 v[70:71], v[56:57], 0, v[70:71]
	s_cbranch_vccz .LBB0_480
	v_mov_b64_e32 v[74:75], s[96:97]
	v_mad_i64_i32 v[72:73], s[14:15], v72, s33, v[74:75]
	s_mov_b32 s7, s94
	v_lshl_add_u64 v[72:73], v[72:73], 0, s[6:7]
	v_lshl_add_u64 v[72:73], v[72:73], 0, v[46:47]
	v_add_co_u32_e32 v72, vcc, 0x1000, v72
	s_nop 0
	v_addc_co_u32_e32 v73, vcc, 0, v73, vcc
	s_mov_b64 s[14:15], 0
	s_waitcnt vmcnt(1)
	v_lshlrev_b32_e32 v74, 16, v242
	v_and_b32_e32 v75, 0xffff0000, v242
	s_waitcnt lgkmcnt(1)
	v_pk_add_f32 v[74:75], v[40:41], v[74:75]
	s_waitcnt vmcnt(0)
	v_lshlrev_b32_e32 v76, 16, v246
	v_mul_f32_e32 v46, 0xbfb8aa3b, v76
	v_exp_f32_e32 v46, v46
	v_and_b32_e32 v77, 0xffff0000, v246
	v_add_f32_e32 v46, 1.0, v46
	v_rcp_f32_e32 v78, v46
	v_mul_f32_e32 v46, 0xbfb8aa3b, v77
	v_exp_f32_e32 v46, v46
	s_nop 0
	v_add_f32_e32 v46, 1.0, v46
	v_rcp_f32_e32 v79, v46
	s_nop 0
	v_pk_mul_f32 v[76:77], v[78:79], v[76:77]
	v_lshlrev_b32_e32 v78, 16, v247
	v_mul_f32_e32 v46, 0xbfb8aa3b, v78
	v_exp_f32_e32 v46, v46
	v_and_b32_e32 v79, 0xffff0000, v247
	v_pk_mul_f32 v[74:75], v[74:75], v[76:77]
	v_lshlrev_b32_e32 v76, 16, v243
	v_add_f32_e32 v46, 1.0, v46
	v_rcp_f32_e32 v242, v46
	v_mul_f32_e32 v46, 0xbfb8aa3b, v79
	v_exp_f32_e32 v46, v46
	v_and_b32_e32 v77, 0xffff0000, v243
	v_pk_add_f32 v[76:77], v[42:43], v[76:77]
	v_cvt_pk_bf16_f32 v74, v74, v75
	v_add_f32_e32 v46, 1.0, v46
	v_rcp_f32_e32 v243, v46
	s_nop 0
	v_pk_mul_f32 v[78:79], v[242:243], v[78:79]
	v_lshlrev_b32_e32 v242, 16, v248
	v_mul_f32_e32 v46, 0xbfb8aa3b, v242
	v_exp_f32_e32 v46, v46
	v_and_b32_e32 v243, 0xffff0000, v248
	v_pk_mul_f32 v[76:77], v[76:77], v[78:79]
	v_lshlrev_b32_e32 v78, 16, v244
	v_add_f32_e32 v46, 1.0, v46
	v_rcp_f32_e32 v246, v46
	v_mul_f32_e32 v46, 0xbfb8aa3b, v243
	v_exp_f32_e32 v46, v46
	v_and_b32_e32 v79, 0xffff0000, v244
	v_lshlrev_b32_e32 v244, 16, v249
	s_waitcnt lgkmcnt(0)
	v_pk_add_f32 v[78:79], v[36:37], v[78:79]
	v_add_f32_e32 v46, 1.0, v46
	v_rcp_f32_e32 v247, v46
	v_mul_f32_e32 v46, 0xbfb8aa3b, v244
	v_exp_f32_e32 v46, v46
	v_cvt_pk_bf16_f32 v75, v76, v77
	v_pk_mul_f32 v[242:243], v[246:247], v[242:243]
	v_add_f32_e32 v46, 1.0, v46
	v_pk_mul_f32 v[78:79], v[78:79], v[242:243]
	v_lshlrev_b32_e32 v242, 16, v245
	v_and_b32_e32 v243, 0xffff0000, v245
	v_and_b32_e32 v245, 0xffff0000, v249
	v_rcp_f32_e32 v246, v46
	v_mul_f32_e32 v46, 0xbfb8aa3b, v245
	v_exp_f32_e32 v46, v46
	v_pk_add_f32 v[242:243], v[38:39], v[242:243]
	v_cvt_pk_bf16_f32 v76, v78, v79
	v_add_f32_e32 v46, 1.0, v46
	v_rcp_f32_e32 v247, v46
	s_nop 0
	v_pk_mul_f32 v[244:245], v[246:247], v[244:245]
	s_nop 0
	v_pk_mul_f32 v[242:243], v[242:243], v[244:245]
	s_nop 0
	v_cvt_pk_bf16_f32 v77, v242, v243
	global_store_dwordx4 v[72:73], v[74:77], off offset:2048
